# speedup vs baseline: 1.0068x; 1.0068x over previous
.LBB0_1507:
	ds_read_b128 v[44:47], v160
	ds_read_b128 v[48:51], v160 offset:16
	ds_read_b128 v[56:59], v160 offset:8704
	ds_read_b128 v[60:63], v160 offset:8720
	ds_read_b128 v[64:67], v160 offset:17408
	ds_read_b128 v[68:71], v160 offset:17424
	ds_read_b128 v[72:75], v160 offset:26112
	ds_read_b128 v[76:79], v160 offset:26128
	ds_read_b128 v[100:103], v160 offset:34816
	ds_read_b128 v[104:107], v160 offset:34832
	ds_read_b64 v[108:109], v158
	s_waitcnt lgkmcnt(14)
	v_pk_mul_f32 v[110:111], v[36:37], v[88:89]
	v_pk_mul_f32 v[112:113], v[38:39], v[92:93]
	v_pk_fma_f32 v[110:111], v[32:33], v[94:95], v[110:111]
	v_pk_fma_f32 v[112:113], v[34:35], v[96:97], v[112:113]
	v_pk_mul_f32 v[36:37], v[36:37], v[52:53]
	v_pk_add_f32 v[110:111], v[110:111], v[112:113]
	v_pk_mul_f32 v[38:39], v[38:39], v[54:55]
	v_add_f32_e32 v110, v110, v111
	v_pk_fma_f32 v[32:33], v[32:33], v[40:41], v[36:37]
	v_pk_fma_f32 v[34:35], v[34:35], v[42:43], v[38:39]
	v_add_f32_dpp v110, v110, v110 quad_perm:[1,0,3,2] row_mask:0xf bank_mask:0xf bound_ctrl:1
	v_pk_add_f32 v[32:33], v[32:33], v[34:35]
	s_nop 0
	v_add_f32_dpp v110, v110, v110 quad_perm:[2,3,0,1] row_mask:0xf bank_mask:0xf bound_ctrl:1
	v_add_f32_e32 v32, v32, v33
	s_nop 0
	v_add_f32_dpp v110, v110, v110 row_half_mirror row_mask:0xf bank_mask:0xf bound_ctrl:1
	v_pk_mul_f32 v[112:113], v[24:25], v[110:111] op_sel_hi:[1,0] neg_lo:[0,1] neg_hi:[0,1]
	v_add_f32_dpp v32, v32, v32 quad_perm:[1,0,3,2] row_mask:0xf bank_mask:0xf bound_ctrl:1
	v_pk_fma_f32 v[88:89], v[28:29], v[88:89], v[112:113]
	s_nop 0
	v_add_f32_dpp v32, v32, v32 quad_perm:[2,3,0,1] row_mask:0xf bank_mask:0xf bound_ctrl:1
	s_waitcnt lgkmcnt(11)
	v_pk_fma_f32 v[112:113], v[20:21], v[98:99], v[88:89] op_sel_hi:[1,0,1]
	v_pk_mul_f32 v[88:89], v[26:27], v[110:111] op_sel_hi:[1,0] neg_lo:[0,1] neg_hi:[0,1]
	v_add_f32_dpp v32, v32, v32 row_half_mirror row_mask:0xf bank_mask:0xf bound_ctrl:1
	v_pk_fma_f32 v[88:89], v[30:31], v[92:93], v[88:89]
	v_pk_mul_f32 v[24:25], v[24:25], v[32:33] op_sel_hi:[1,0] neg_lo:[0,1] neg_hi:[0,1]
	v_pk_fma_f32 v[114:115], v[22:23], v[98:99], v[88:89] op_sel_hi:[1,0,1]
	v_pk_mul_f32 v[88:89], v[8:9], v[110:111] op_sel_hi:[1,0] neg_lo:[0,1] neg_hi:[0,1]
	v_pk_fma_f32 v[24:25], v[28:29], v[52:53], v[24:25]
	v_pk_mul_f32 v[8:9], v[8:9], v[32:33] op_sel_hi:[1,0] neg_lo:[0,1] neg_hi:[0,1]
	v_pk_fma_f32 v[88:89], v[0:1], v[94:95], v[88:89]
	v_pk_fma_f32 v[52:53], v[20:21], v[98:99], v[24:25] op_sel:[0,1,0]
	v_pk_mul_f32 v[20:21], v[26:27], v[32:33] op_sel_hi:[1,0] neg_lo:[0,1] neg_hi:[0,1]
	v_pk_fma_f32 v[0:1], v[0:1], v[40:41], v[8:9]
	v_pk_fma_f32 v[94:95], v[12:13], v[98:99], v[88:89] op_sel_hi:[1,0,1]
	v_pk_mul_f32 v[88:89], v[10:11], v[110:111] op_sel_hi:[1,0] neg_lo:[0,1] neg_hi:[0,1]
	v_pk_fma_f32 v[20:21], v[30:31], v[54:55], v[20:21]
	v_pk_fma_f32 v[40:41], v[12:13], v[98:99], v[0:1] op_sel:[0,1,0]
	v_pk_mul_f32 v[0:1], v[10:11], v[32:33] op_sel_hi:[1,0] neg_lo:[0,1] neg_hi:[0,1]
	v_pk_fma_f32 v[88:89], v[2:3], v[96:97], v[88:89]
	v_pk_fma_f32 v[54:55], v[22:23], v[98:99], v[20:21] op_sel:[0,1,0]
	v_pk_fma_f32 v[0:1], v[2:3], v[42:43], v[0:1]
	v_pk_fma_f32 v[96:97], v[14:15], v[98:99], v[88:89] op_sel_hi:[1,0,1]
	v_pk_mul_f32 v[88:89], v[16:17], v[112:113]
	v_pk_mul_f32 v[92:93], v[18:19], v[114:115]
	v_pk_fma_f32 v[42:43], v[14:15], v[98:99], v[0:1] op_sel:[0,1,0]
	v_pk_mul_f32 v[0:1], v[16:17], v[52:53]
	v_pk_mul_f32 v[2:3], v[18:19], v[54:55]
	v_pk_fma_f32 v[88:89], v[4:5], v[94:95], v[88:89]
	v_pk_fma_f32 v[92:93], v[6:7], v[96:97], v[92:93]
	v_pk_fma_f32 v[0:1], v[4:5], v[40:41], v[0:1]
	v_pk_fma_f32 v[2:3], v[6:7], v[42:43], v[2:3]
	v_pk_add_f32 v[88:89], v[88:89], v[92:93]
	v_pk_add_f32 v[0:1], v[0:1], v[2:3]
	v_add_f32_e32 v88, v88, v89
	v_add_f32_e32 v89, v0, v1
	s_nop 1
	v_add_f32_dpp v88, v88, v88 quad_perm:[1,0,3,2] row_mask:0xf bank_mask:0xf bound_ctrl:1
	v_add_f32_dpp v89, v89, v89 quad_perm:[1,0,3,2] row_mask:0xf bank_mask:0xf bound_ctrl:1
	v_add_u32_e32 v124, s49, v158
	v_add_u32_e32 v125, s49, v160
	ds_read_b64 v[98:99], v124
	ds_read_b128 v[0:3], v125 offset:34816
	ds_read_b128 v[4:7], v125 offset:26128
	ds_read_b128 v[8:11], v125 offset:26112
	ds_read_b128 v[12:15], v125 offset:34832
	ds_read_b128 v[16:19], v125 offset:17424
	ds_read_b128 v[20:23], v125 offset:17408
	ds_read_b128 v[24:27], v125 offset:8720
	ds_read_b128 v[28:31], v125 offset:8704
	ds_read_b128 v[32:35], v125 offset:16
	ds_read_b128 v[36:39], v125
	s_waitcnt lgkmcnt(14)
	v_pk_mul_f32 v[110:111], v[56:57], v[112:113]
	v_pk_mul_f32 v[116:117], v[58:59], v[114:115]
	v_pk_mul_f32 v[56:57], v[56:57], v[52:53]
	v_pk_mul_f32 v[58:59], v[58:59], v[54:55]
	v_pk_fma_f32 v[110:111], v[60:61], v[94:95], v[110:111]
	v_pk_fma_f32 v[116:117], v[62:63], v[96:97], v[116:117]
	v_pk_fma_f32 v[56:57], v[60:61], v[40:41], v[56:57]
	v_pk_fma_f32 v[58:59], v[62:63], v[42:43], v[58:59]
	v_pk_add_f32 v[110:111], v[110:111], v[116:117]
	v_pk_add_f32 v[56:57], v[56:57], v[58:59]
	v_add_f32_e32 v110, v110, v111
	v_add_f32_e32 v56, v56, v57
	s_nop 0
	v_add_f32_dpp v110, v110, v110 quad_perm:[1,0,3,2] row_mask:0xf bank_mask:0xf bound_ctrl:1
	v_add_f32_dpp v56, v56, v56 quad_perm:[1,0,3,2] row_mask:0xf bank_mask:0xf bound_ctrl:1
	s_nop 0
	v_add_f32_dpp v110, v110, v110 quad_perm:[2,3,0,1] row_mask:0xf bank_mask:0xf bound_ctrl:1
	v_add_f32_dpp v56, v56, v56 quad_perm:[2,3,0,1] row_mask:0xf bank_mask:0xf bound_ctrl:1
	s_nop 0
	v_add_f32_dpp v110, v110, v110 row_half_mirror row_mask:0xf bank_mask:0xf bound_ctrl:1
	v_add_f32_dpp v56, v56, v56 row_half_mirror row_mask:0xf bank_mask:0xf bound_ctrl:1
	v_pk_mul_f32 v[116:117], v[64:65], v[110:111] op_sel_hi:[1,0] neg_lo:[0,1] neg_hi:[0,1]
	v_pk_mul_f32 v[58:59], v[64:65], v[56:57] op_sel_hi:[1,0] neg_lo:[0,1] neg_hi:[0,1]
	v_pk_fma_f32 v[112:113], v[44:45], v[112:113], v[116:117]
	v_pk_fma_f32 v[44:45], v[44:45], v[52:53], v[58:59]
	v_pk_mul_f32 v[116:117], v[66:67], v[110:111] op_sel_hi:[1,0] neg_lo:[0,1] neg_hi:[0,1]
	s_waitcnt lgkmcnt(11)
	v_pk_fma_f32 v[118:119], v[72:73], v[108:109], v[44:45] op_sel:[0,1,0]
	v_pk_mul_f32 v[44:45], v[66:67], v[56:57] op_sel_hi:[1,0] neg_lo:[0,1] neg_hi:[0,1]
	v_pk_fma_f32 v[114:115], v[46:47], v[114:115], v[116:117]
	v_pk_fma_f32 v[44:45], v[46:47], v[54:55], v[44:45]
	v_pk_mul_f32 v[116:117], v[68:69], v[110:111] op_sel_hi:[1,0] neg_lo:[0,1] neg_hi:[0,1]
	v_pk_fma_f32 v[120:121], v[74:75], v[108:109], v[44:45] op_sel:[0,1,0]
	v_pk_mul_f32 v[44:45], v[68:69], v[56:57] op_sel_hi:[1,0] neg_lo:[0,1] neg_hi:[0,1]
	v_pk_fma_f32 v[94:95], v[48:49], v[94:95], v[116:117]
	v_pk_fma_f32 v[40:41], v[48:49], v[40:41], v[44:45]
	v_pk_fma_f32 v[116:117], v[76:77], v[108:109], v[94:95] op_sel_hi:[1,0,1]
	v_pk_mul_f32 v[94:95], v[70:71], v[110:111] op_sel_hi:[1,0] neg_lo:[0,1] neg_hi:[0,1]
	v_pk_fma_f32 v[122:123], v[76:77], v[108:109], v[40:41] op_sel:[0,1,0]
	v_pk_mul_f32 v[40:41], v[70:71], v[56:57] op_sel_hi:[1,0] neg_lo:[0,1] neg_hi:[0,1]
	v_pk_fma_f32 v[112:113], v[72:73], v[108:109], v[112:113] op_sel_hi:[1,0,1]
	v_pk_fma_f32 v[114:115], v[74:75], v[108:109], v[114:115] op_sel_hi:[1,0,1]
	v_pk_fma_f32 v[94:95], v[50:51], v[96:97], v[94:95]
	v_pk_fma_f32 v[40:41], v[50:51], v[42:43], v[40:41]
	v_pk_fma_f32 v[110:111], v[78:79], v[108:109], v[94:95] op_sel_hi:[1,0,1]
	v_pk_mul_f32 v[94:95], v[100:101], v[112:113]
	v_pk_mul_f32 v[96:97], v[102:103], v[114:115]
	v_pk_fma_f32 v[108:109], v[78:79], v[108:109], v[40:41] op_sel:[0,1,0]
	v_pk_mul_f32 v[40:41], v[100:101], v[118:119]
	v_pk_mul_f32 v[42:43], v[102:103], v[120:121]
	v_pk_fma_f32 v[94:95], v[104:105], v[116:117], v[94:95]
	v_pk_fma_f32 v[96:97], v[106:107], v[110:111], v[96:97]
	v_pk_fma_f32 v[40:41], v[104:105], v[122:123], v[40:41]
	v_pk_fma_f32 v[42:43], v[106:107], v[108:109], v[42:43]
	v_pk_add_f32 v[94:95], v[94:95], v[96:97]
	v_pk_add_f32 v[96:97], v[40:41], v[42:43]
	v_add_u32_e32 v125, s49, v125
	ds_read_b128 v[40:43], v125
	ds_read_b128 v[44:47], v125 offset:16
	ds_read_b128 v[48:51], v125 offset:8704
	ds_read_b128 v[52:55], v125 offset:8720
	ds_read_b128 v[56:59], v125 offset:17408
	ds_read_b128 v[60:63], v125 offset:17424
	ds_read_b128 v[64:67], v125 offset:26112
	ds_read_b128 v[68:71], v125 offset:26128
	ds_read_b128 v[72:75], v125 offset:34816
	ds_read_b128 v[76:79], v125 offset:34832
	v_add_u32_e32 v124, s49, v124
	ds_read_b64 v[104:105], v124
	s_waitcnt lgkmcnt(13)
	v_pk_mul_f32 v[100:101], v[28:29], v[112:113]
	v_pk_mul_f32 v[102:103], v[30:31], v[114:115]
	v_pk_fma_f32 v[100:101], v[24:25], v[116:117], v[100:101]
	v_pk_fma_f32 v[102:103], v[26:27], v[110:111], v[102:103]
	v_pk_mul_f32 v[28:29], v[28:29], v[118:119]
	v_pk_add_f32 v[100:101], v[100:101], v[102:103]
	v_pk_mul_f32 v[30:31], v[30:31], v[120:121]
	v_add_f32_e32 v100, v100, v101
	v_pk_fma_f32 v[24:25], v[24:25], v[122:123], v[28:29]
	v_pk_fma_f32 v[26:27], v[26:27], v[108:109], v[30:31]
	v_add_f32_dpp v100, v100, v100 quad_perm:[1,0,3,2] row_mask:0xf bank_mask:0xf bound_ctrl:1
	v_pk_add_f32 v[24:25], v[24:25], v[26:27]
	s_nop 0
	v_add_f32_dpp v100, v100, v100 quad_perm:[2,3,0,1] row_mask:0xf bank_mask:0xf bound_ctrl:1
	v_add_f32_e32 v24, v24, v25
	s_nop 0
	v_add_f32_dpp v100, v100, v100 row_half_mirror row_mask:0xf bank_mask:0xf bound_ctrl:1
	v_pk_mul_f32 v[102:103], v[20:21], v[100:101] op_sel_hi:[1,0] neg_lo:[0,1] neg_hi:[0,1]
	v_add_f32_dpp v24, v24, v24 quad_perm:[1,0,3,2] row_mask:0xf bank_mask:0xf bound_ctrl:1
	s_waitcnt lgkmcnt(11)
	v_pk_fma_f32 v[102:103], v[36:37], v[112:113], v[102:103]
	v_add_f32_dpp v24, v24, v24 quad_perm:[2,3,0,1] row_mask:0xf bank_mask:0xf bound_ctrl:1
	v_pk_fma_f32 v[106:107], v[98:99], v[8:9], v[102:103] op_sel_hi:[0,1,1]
	v_pk_mul_f32 v[102:103], v[22:23], v[100:101] op_sel_hi:[1,0] neg_lo:[0,1] neg_hi:[0,1]
	v_add_f32_dpp v24, v24, v24 row_half_mirror row_mask:0xf bank_mask:0xf bound_ctrl:1
	v_pk_fma_f32 v[102:103], v[38:39], v[114:115], v[102:103]
	v_pk_mul_f32 v[20:21], v[20:21], v[24:25] op_sel_hi:[1,0] neg_lo:[0,1] neg_hi:[0,1]
	v_pk_fma_f32 v[112:113], v[98:99], v[10:11], v[102:103] op_sel_hi:[0,1,1]
	v_pk_mul_f32 v[102:103], v[16:17], v[100:101] op_sel_hi:[1,0] neg_lo:[0,1] neg_hi:[0,1]
	v_pk_fma_f32 v[20:21], v[36:37], v[118:119], v[20:21]
	v_pk_fma_f32 v[102:103], v[32:33], v[116:117], v[102:103]
	v_pk_fma_f32 v[116:117], v[98:99], v[8:9], v[20:21] op_sel:[1,0,0]
	v_pk_mul_f32 v[8:9], v[22:23], v[24:25] op_sel_hi:[1,0] neg_lo:[0,1] neg_hi:[0,1]
	v_pk_fma_f32 v[114:115], v[98:99], v[4:5], v[102:103] op_sel_hi:[0,1,1]
	v_pk_fma_f32 v[8:9], v[38:39], v[120:121], v[8:9]
	v_pk_mul_f32 v[100:101], v[18:19], v[100:101] op_sel_hi:[1,0] neg_lo:[0,1] neg_hi:[0,1]
	v_pk_fma_f32 v[118:119], v[98:99], v[10:11], v[8:9] op_sel:[1,0,0]
	v_pk_mul_f32 v[8:9], v[16:17], v[24:25] op_sel_hi:[1,0] neg_lo:[0,1] neg_hi:[0,1]
	v_pk_fma_f32 v[100:101], v[34:35], v[110:111], v[100:101]
	v_pk_fma_f32 v[8:9], v[32:33], v[122:123], v[8:9]
	v_pk_fma_f32 v[110:111], v[98:99], v[6:7], v[100:101] op_sel_hi:[0,1,1]
	v_pk_fma_f32 v[120:121], v[98:99], v[4:5], v[8:9] op_sel:[1,0,0]
	v_pk_mul_f32 v[4:5], v[18:19], v[24:25] op_sel_hi:[1,0] neg_lo:[0,1] neg_hi:[0,1]
	v_pk_mul_f32 v[100:101], v[0:1], v[106:107]
	v_pk_fma_f32 v[4:5], v[34:35], v[108:109], v[4:5]
	v_pk_mul_f32 v[102:103], v[2:3], v[112:113]
	v_pk_fma_f32 v[98:99], v[98:99], v[6:7], v[4:5] op_sel:[1,0,0]
	v_pk_mul_f32 v[0:1], v[0:1], v[116:117]
	v_pk_mul_f32 v[2:3], v[2:3], v[118:119]
	v_pk_fma_f32 v[100:101], v[12:13], v[114:115], v[100:101]
	v_pk_fma_f32 v[102:103], v[14:15], v[110:111], v[102:103]
	v_pk_fma_f32 v[0:1], v[12:13], v[120:121], v[0:1]
	v_pk_fma_f32 v[2:3], v[14:15], v[98:99], v[2:3]
	v_pk_add_f32 v[100:101], v[100:101], v[102:103]
	v_pk_add_f32 v[102:103], v[0:1], v[2:3]
	v_add_u32_e32 v126, s49, v124
	v_add_u32_e32 v127, s49, v125
	ds_read_b64 v[122:123], v126
	ds_read_b128 v[0:3], v127 offset:34832
	ds_read_b128 v[4:7], v127 offset:34816
	ds_read_b128 v[8:11], v127 offset:26128
	ds_read_b128 v[12:15], v127 offset:26112
	ds_read_b128 v[16:19], v127 offset:17424
	ds_read_b128 v[20:23], v127 offset:17408
	ds_read_b128 v[24:27], v127 offset:8720
	ds_read_b128 v[28:31], v127 offset:8704
	ds_read_b128 v[32:35], v127 offset:16
	ds_read_b128 v[36:39], v127
	s_waitcnt lgkmcnt(14)
	v_pk_mul_f32 v[108:109], v[48:49], v[106:107]
	v_pk_mul_f32 v[124:125], v[50:51], v[112:113]
	v_pk_mul_f32 v[48:49], v[48:49], v[116:117]
	v_pk_mul_f32 v[50:51], v[50:51], v[118:119]
	v_pk_fma_f32 v[108:109], v[52:53], v[114:115], v[108:109]
	v_pk_fma_f32 v[124:125], v[54:55], v[110:111], v[124:125]
	v_pk_fma_f32 v[48:49], v[52:53], v[120:121], v[48:49]
	v_pk_fma_f32 v[50:51], v[54:55], v[98:99], v[50:51]
	v_pk_add_f32 v[108:109], v[108:109], v[124:125]
	v_pk_add_f32 v[48:49], v[48:49], v[50:51]
	v_add_f32_e32 v108, v108, v109
	v_add_f32_e32 v48, v48, v49
	s_nop 0
	v_add_f32_dpp v108, v108, v108 quad_perm:[1,0,3,2] row_mask:0xf bank_mask:0xf bound_ctrl:1
	v_add_f32_dpp v48, v48, v48 quad_perm:[1,0,3,2] row_mask:0xf bank_mask:0xf bound_ctrl:1
	s_nop 0
	v_add_f32_dpp v108, v108, v108 quad_perm:[2,3,0,1] row_mask:0xf bank_mask:0xf bound_ctrl:1
	v_add_f32_dpp v48, v48, v48 quad_perm:[2,3,0,1] row_mask:0xf bank_mask:0xf bound_ctrl:1
	s_nop 0
	v_add_f32_dpp v108, v108, v108 row_half_mirror row_mask:0xf bank_mask:0xf bound_ctrl:1
	v_add_f32_dpp v48, v48, v48 row_half_mirror row_mask:0xf bank_mask:0xf bound_ctrl:1
	v_pk_mul_f32 v[124:125], v[56:57], v[108:109] op_sel_hi:[1,0] neg_lo:[0,1] neg_hi:[0,1]
	v_pk_mul_f32 v[50:51], v[56:57], v[48:49] op_sel_hi:[1,0] neg_lo:[0,1] neg_hi:[0,1]
	v_pk_fma_f32 v[106:107], v[40:41], v[106:107], v[124:125]
	v_pk_fma_f32 v[40:41], v[40:41], v[116:117], v[50:51]
	s_waitcnt lgkmcnt(11)
	v_pk_fma_f32 v[124:125], v[64:65], v[104:105], v[106:107] op_sel_hi:[1,0,1]
	v_pk_mul_f32 v[106:107], v[58:59], v[108:109] op_sel_hi:[1,0] neg_lo:[0,1] neg_hi:[0,1]
	v_pk_fma_f32 v[116:117], v[64:65], v[104:105], v[40:41] op_sel:[0,1,0]
	v_pk_mul_f32 v[40:41], v[58:59], v[48:49] op_sel_hi:[1,0] neg_lo:[0,1] neg_hi:[0,1]
	v_pk_fma_f32 v[106:107], v[42:43], v[112:113], v[106:107]
	v_pk_fma_f32 v[40:41], v[42:43], v[118:119], v[40:41]
	v_pk_fma_f32 v[112:113], v[66:67], v[104:105], v[106:107] op_sel_hi:[1,0,1]
	v_pk_mul_f32 v[106:107], v[60:61], v[108:109] op_sel_hi:[1,0] neg_lo:[0,1] neg_hi:[0,1]
	v_pk_fma_f32 v[118:119], v[66:67], v[104:105], v[40:41] op_sel:[0,1,0]
	v_pk_mul_f32 v[40:41], v[60:61], v[48:49] op_sel_hi:[1,0] neg_lo:[0,1] neg_hi:[0,1]
	v_pk_fma_f32 v[106:107], v[44:45], v[114:115], v[106:107]
	v_pk_fma_f32 v[40:41], v[44:45], v[120:121], v[40:41]
	v_pk_fma_f32 v[114:115], v[68:69], v[104:105], v[106:107] op_sel_hi:[1,0,1]
	v_pk_mul_f32 v[106:107], v[62:63], v[108:109] op_sel_hi:[1,0] neg_lo:[0,1] neg_hi:[0,1]
	v_pk_fma_f32 v[120:121], v[68:69], v[104:105], v[40:41] op_sel:[0,1,0]
	v_pk_mul_f32 v[40:41], v[62:63], v[48:49] op_sel_hi:[1,0] neg_lo:[0,1] neg_hi:[0,1]
	v_pk_fma_f32 v[106:107], v[46:47], v[110:111], v[106:107]
	v_pk_fma_f32 v[40:41], v[46:47], v[98:99], v[40:41]
	v_pk_fma_f32 v[110:111], v[70:71], v[104:105], v[106:107] op_sel_hi:[1,0,1]
	v_pk_mul_f32 v[106:107], v[72:73], v[124:125]
	v_pk_mul_f32 v[108:109], v[74:75], v[112:113]
	v_pk_fma_f32 v[98:99], v[70:71], v[104:105], v[40:41] op_sel:[0,1,0]
	v_pk_mul_f32 v[40:41], v[72:73], v[116:117]
	v_pk_mul_f32 v[42:43], v[74:75], v[118:119]
	v_pk_fma_f32 v[106:107], v[76:77], v[114:115], v[106:107]
	v_pk_fma_f32 v[108:109], v[78:79], v[110:111], v[108:109]
	v_pk_fma_f32 v[40:41], v[76:77], v[120:121], v[40:41]
	v_pk_fma_f32 v[42:43], v[78:79], v[98:99], v[42:43]
	v_pk_add_f32 v[106:107], v[106:107], v[108:109]
	v_pk_add_f32 v[108:109], v[40:41], v[42:43]
	v_add_u32_e32 v130, s49, v127
	ds_read_b128 v[40:43], v130
	ds_read_b128 v[44:47], v130 offset:16
	ds_read_b128 v[48:51], v130 offset:8704
	ds_read_b128 v[52:55], v130 offset:8720
	ds_read_b128 v[56:59], v130 offset:17408
	ds_read_b128 v[60:63], v130 offset:17424
	ds_read_b128 v[64:67], v130 offset:26112
	ds_read_b128 v[68:71], v130 offset:26128
	ds_read_b128 v[72:75], v130 offset:34816
	ds_read_b128 v[76:79], v130 offset:34832
	v_add_u32_e32 v131, s49, v126
	ds_read_b64 v[104:105], v131
	s_waitcnt lgkmcnt(13)
	v_pk_mul_f32 v[126:127], v[28:29], v[124:125]
	v_pk_mul_f32 v[128:129], v[30:31], v[112:113]
	v_pk_mul_f32 v[28:29], v[28:29], v[116:117]
	v_pk_mul_f32 v[30:31], v[30:31], v[118:119]
	v_pk_fma_f32 v[126:127], v[24:25], v[114:115], v[126:127]
	v_pk_fma_f32 v[128:129], v[26:27], v[110:111], v[128:129]
	v_pk_fma_f32 v[24:25], v[24:25], v[120:121], v[28:29]
	v_pk_fma_f32 v[26:27], v[26:27], v[98:99], v[30:31]
	v_pk_add_f32 v[126:127], v[126:127], v[128:129]
	v_pk_add_f32 v[24:25], v[24:25], v[26:27]
	v_add_f32_e32 v126, v126, v127
	v_add_f32_e32 v24, v24, v25
	s_nop 0
	v_add_f32_dpp v126, v126, v126 quad_perm:[1,0,3,2] row_mask:0xf bank_mask:0xf bound_ctrl:1
	v_add_f32_dpp v24, v24, v24 quad_perm:[1,0,3,2] row_mask:0xf bank_mask:0xf bound_ctrl:1
	s_nop 0
	v_add_f32_dpp v126, v126, v126 quad_perm:[2,3,0,1] row_mask:0xf bank_mask:0xf bound_ctrl:1
	v_add_f32_dpp v24, v24, v24 quad_perm:[2,3,0,1] row_mask:0xf bank_mask:0xf bound_ctrl:1
	s_nop 0
	v_add_f32_dpp v126, v126, v126 row_half_mirror row_mask:0xf bank_mask:0xf bound_ctrl:1
	v_add_f32_dpp v24, v24, v24 row_half_mirror row_mask:0xf bank_mask:0xf bound_ctrl:1
	v_pk_mul_f32 v[128:129], v[20:21], v[126:127] op_sel_hi:[1,0] neg_lo:[0,1] neg_hi:[0,1]
	v_pk_mul_f32 v[20:21], v[20:21], v[24:25] op_sel_hi:[1,0] neg_lo:[0,1] neg_hi:[0,1]
	s_waitcnt lgkmcnt(11)
	v_pk_fma_f32 v[124:125], v[36:37], v[124:125], v[128:129]
	v_pk_fma_f32 v[20:21], v[36:37], v[116:117], v[20:21]
	v_pk_fma_f32 v[124:125], v[122:123], v[12:13], v[124:125] op_sel_hi:[0,1,1]
	v_pk_fma_f32 v[116:117], v[122:123], v[12:13], v[20:21] op_sel:[1,0,0]
	v_pk_mul_f32 v[12:13], v[22:23], v[24:25] op_sel_hi:[1,0] neg_lo:[0,1] neg_hi:[0,1]
	v_pk_mul_f32 v[128:129], v[22:23], v[126:127] op_sel_hi:[1,0] neg_lo:[0,1] neg_hi:[0,1]
	v_pk_fma_f32 v[12:13], v[38:39], v[118:119], v[12:13]
	v_pk_fma_f32 v[112:113], v[38:39], v[112:113], v[128:129]
	v_pk_mul_f32 v[128:129], v[16:17], v[126:127] op_sel_hi:[1,0] neg_lo:[0,1] neg_hi:[0,1]
	v_pk_fma_f32 v[118:119], v[122:123], v[14:15], v[12:13] op_sel:[1,0,0]
	v_pk_mul_f32 v[12:13], v[16:17], v[24:25] op_sel_hi:[1,0] neg_lo:[0,1] neg_hi:[0,1]
	v_pk_fma_f32 v[114:115], v[32:33], v[114:115], v[128:129]
	v_pk_fma_f32 v[12:13], v[32:33], v[120:121], v[12:13]
	v_pk_fma_f32 v[114:115], v[122:123], v[8:9], v[114:115] op_sel_hi:[0,1,1]
	v_pk_mul_f32 v[126:127], v[18:19], v[126:127] op_sel_hi:[1,0] neg_lo:[0,1] neg_hi:[0,1]
	v_pk_fma_f32 v[120:121], v[122:123], v[8:9], v[12:13] op_sel:[1,0,0]
	v_pk_mul_f32 v[8:9], v[18:19], v[24:25] op_sel_hi:[1,0] neg_lo:[0,1] neg_hi:[0,1]
	v_pk_fma_f32 v[112:113], v[122:123], v[14:15], v[112:113] op_sel_hi:[0,1,1]
	v_pk_fma_f32 v[110:111], v[34:35], v[110:111], v[126:127]
	v_pk_fma_f32 v[8:9], v[34:35], v[98:99], v[8:9]
	v_pk_fma_f32 v[110:111], v[122:123], v[10:11], v[110:111] op_sel_hi:[0,1,1]
	v_pk_mul_f32 v[126:127], v[4:5], v[124:125]
	v_pk_mul_f32 v[128:129], v[6:7], v[112:113]
	v_pk_fma_f32 v[122:123], v[122:123], v[10:11], v[8:9] op_sel:[1,0,0]
	v_pk_mul_f32 v[4:5], v[4:5], v[116:117]
	v_pk_mul_f32 v[6:7], v[6:7], v[118:119]
	v_pk_fma_f32 v[126:127], v[0:1], v[114:115], v[126:127]
	v_pk_fma_f32 v[128:129], v[2:3], v[110:111], v[128:129]
	v_pk_fma_f32 v[0:1], v[0:1], v[120:121], v[4:5]
	v_pk_fma_f32 v[2:3], v[2:3], v[122:123], v[6:7]
	v_pk_add_f32 v[126:127], v[126:127], v[128:129]
	v_pk_add_f32 v[128:129], v[0:1], v[2:3]
	v_add_u32_e32 v161, s49, v131
	v_add_u32_e32 v170, s49, v130
	ds_read_b64 v[98:99], v161
	ds_read_b128 v[4:7], v170 offset:34832
	ds_read_b128 v[16:19], v170 offset:34816
	ds_read_b128 v[12:15], v170 offset:26128
	ds_read_b128 v[20:23], v170 offset:26112
	ds_read_b128 v[8:11], v170 offset:17424
	ds_read_b128 v[24:27], v170 offset:17408
	ds_read_b128 v[32:35], v170 offset:8720
	ds_read_b128 v[36:39], v170 offset:8704
	ds_read_b128 v[0:3], v170 offset:16
	ds_read_b128 v[28:31], v170
	s_waitcnt lgkmcnt(14)
	v_pk_mul_f32 v[130:131], v[48:49], v[124:125]
	v_pk_mul_f32 v[132:133], v[50:51], v[112:113]
	v_pk_mul_f32 v[48:49], v[48:49], v[116:117]
	v_pk_mul_f32 v[50:51], v[50:51], v[118:119]
	v_pk_fma_f32 v[130:131], v[52:53], v[114:115], v[130:131]
	v_pk_fma_f32 v[132:133], v[54:55], v[110:111], v[132:133]
	v_pk_fma_f32 v[48:49], v[52:53], v[120:121], v[48:49]
	v_pk_fma_f32 v[50:51], v[54:55], v[122:123], v[50:51]
	v_pk_add_f32 v[130:131], v[130:131], v[132:133]
	v_pk_add_f32 v[48:49], v[48:49], v[50:51]
	v_add_f32_e32 v130, v130, v131
	v_add_f32_e32 v48, v48, v49
	s_nop 0
	v_add_f32_dpp v130, v130, v130 quad_perm:[1,0,3,2] row_mask:0xf bank_mask:0xf bound_ctrl:1
	v_add_f32_dpp v48, v48, v48 quad_perm:[1,0,3,2] row_mask:0xf bank_mask:0xf bound_ctrl:1
	s_nop 0
	v_add_f32_dpp v130, v130, v130 quad_perm:[2,3,0,1] row_mask:0xf bank_mask:0xf bound_ctrl:1
	v_add_f32_dpp v48, v48, v48 quad_perm:[2,3,0,1] row_mask:0xf bank_mask:0xf bound_ctrl:1
	s_nop 0
	v_add_f32_dpp v130, v130, v130 row_half_mirror row_mask:0xf bank_mask:0xf bound_ctrl:1
	v_add_f32_dpp v48, v48, v48 row_half_mirror row_mask:0xf bank_mask:0xf bound_ctrl:1
	v_pk_mul_f32 v[132:133], v[56:57], v[130:131] op_sel_hi:[1,0] neg_lo:[0,1] neg_hi:[0,1]
	v_pk_mul_f32 v[50:51], v[56:57], v[48:49] op_sel_hi:[1,0] neg_lo:[0,1] neg_hi:[0,1]
	v_pk_fma_f32 v[124:125], v[40:41], v[124:125], v[132:133]
	v_pk_fma_f32 v[40:41], v[40:41], v[116:117], v[50:51]
	v_pk_mul_f32 v[132:133], v[58:59], v[130:131] op_sel_hi:[1,0] neg_lo:[0,1] neg_hi:[0,1]
	s_waitcnt lgkmcnt(11)
	v_pk_fma_f32 v[134:135], v[64:65], v[104:105], v[40:41] op_sel:[0,1,0]
	v_pk_mul_f32 v[40:41], v[58:59], v[48:49] op_sel_hi:[1,0] neg_lo:[0,1] neg_hi:[0,1]
	v_pk_fma_f32 v[112:113], v[42:43], v[112:113], v[132:133]
	v_pk_fma_f32 v[40:41], v[42:43], v[118:119], v[40:41]
	v_pk_mul_f32 v[132:133], v[60:61], v[130:131] op_sel_hi:[1,0] neg_lo:[0,1] neg_hi:[0,1]
	v_pk_fma_f32 v[136:137], v[66:67], v[104:105], v[40:41] op_sel:[0,1,0]
	v_pk_mul_f32 v[40:41], v[60:61], v[48:49] op_sel_hi:[1,0] neg_lo:[0,1] neg_hi:[0,1]
	v_pk_mul_f32 v[130:131], v[62:63], v[130:131] op_sel_hi:[1,0] neg_lo:[0,1] neg_hi:[0,1]
	v_pk_fma_f32 v[40:41], v[44:45], v[120:121], v[40:41]
	v_pk_fma_f32 v[124:125], v[64:65], v[104:105], v[124:125] op_sel_hi:[1,0,1]
	v_pk_fma_f32 v[112:113], v[66:67], v[104:105], v[112:113] op_sel_hi:[1,0,1]
	v_pk_fma_f32 v[114:115], v[44:45], v[114:115], v[132:133]
	v_pk_fma_f32 v[110:111], v[46:47], v[110:111], v[130:131]
	v_pk_fma_f32 v[162:163], v[68:69], v[104:105], v[40:41] op_sel:[0,1,0]
	v_pk_mul_f32 v[40:41], v[62:63], v[48:49] op_sel_hi:[1,0] neg_lo:[0,1] neg_hi:[0,1]
	v_pk_fma_f32 v[114:115], v[68:69], v[104:105], v[114:115] op_sel_hi:[1,0,1]
	v_pk_fma_f32 v[130:131], v[70:71], v[104:105], v[110:111] op_sel_hi:[1,0,1]
	v_pk_mul_f32 v[110:111], v[72:73], v[124:125]
	v_pk_mul_f32 v[132:133], v[74:75], v[112:113]
	v_pk_fma_f32 v[40:41], v[46:47], v[122:123], v[40:41]
	v_pk_fma_f32 v[110:111], v[76:77], v[114:115], v[110:111]
	v_pk_fma_f32 v[132:133], v[78:79], v[130:131], v[132:133]
	v_pk_fma_f32 v[166:167], v[70:71], v[104:105], v[40:41] op_sel:[0,1,0]
	v_pk_mul_f32 v[40:41], v[72:73], v[134:135]
	v_pk_mul_f32 v[42:43], v[74:75], v[136:137]
	v_pk_add_f32 v[132:133], v[110:111], v[132:133]
	v_pk_fma_f32 v[40:41], v[76:77], v[162:163], v[40:41]
	v_pk_fma_f32 v[42:43], v[78:79], v[166:167], v[42:43]
	s_nop 0
	v_pk_add_f32 v[168:169], v[40:41], v[42:43]
	v_add_u32_e32 v44, s49, v170
	ds_read_b128 v[52:55], v44
	ds_read_b128 v[40:43], v44 offset:16
	ds_read_b128 v[76:79], v44 offset:8704
	ds_read_b128 v[72:75], v44 offset:8720
	ds_read_b128 v[64:67], v44 offset:17408
	ds_read_b128 v[56:59], v44 offset:17424
	ds_read_b128 v[68:71], v44 offset:26112
	ds_read_b128 v[60:63], v44 offset:26128
	ds_read_b128 v[48:51], v44 offset:34816
	ds_read_b128 v[44:47], v44 offset:34832
	v_add_u32_e32 v104, s49, v161
	ds_read_b64 v[104:105], v104
	s_waitcnt lgkmcnt(13)
	v_pk_mul_f32 v[110:111], v[36:37], v[124:125]
	v_pk_mul_f32 v[116:117], v[38:39], v[112:113]
	v_pk_fma_f32 v[110:111], v[32:33], v[114:115], v[110:111]
	v_pk_fma_f32 v[116:117], v[34:35], v[130:131], v[116:117]
	s_nop 0
	v_pk_add_f32 v[110:111], v[110:111], v[116:117]
	s_nop 0
	v_add_f32_e32 v110, v110, v111
	v_add_f32_dpp v88, v88, v88 quad_perm:[2,3,0,1] row_mask:0xf bank_mask:0xf bound_ctrl:1
	v_add_f32_dpp v89, v89, v89 quad_perm:[2,3,0,1] row_mask:0xf bank_mask:0xf bound_ctrl:1
	v_add_f32_dpp v110, v110, v110 quad_perm:[1,0,3,2] row_mask:0xf bank_mask:0xf bound_ctrl:1
	s_nop 0
	s_nop 0
	v_add_f32_dpp v110, v110, v110 quad_perm:[2,3,0,1] row_mask:0xf bank_mask:0xf bound_ctrl:1
	v_add_f32_dpp v88, v88, v88 row_half_mirror row_mask:0xf bank_mask:0xf bound_ctrl:1
	v_add_f32_dpp v89, v89, v89 row_half_mirror row_mask:0xf bank_mask:0xf bound_ctrl:1
	v_add_f32_dpp v116, v110, v110 row_half_mirror row_mask:0xf bank_mask:0xf bound_ctrl:1
	v_pk_mul_f32 v[110:111], v[24:25], v[116:117] op_sel_hi:[1,0] neg_lo:[0,1] neg_hi:[0,1]
	v_pk_mul_f32 v[118:119], v[26:27], v[116:117] op_sel_hi:[1,0] neg_lo:[0,1] neg_hi:[0,1]
	s_waitcnt lgkmcnt(11)
; #define SBAR() __builtin_amdgcn_sched_barrier(0)
; #define STEP(X, ii) do { ROWSTEP(X, S0, X##vv[0], yk0, ii); ROWSTEP(X, S1, X##vv[1], yk1, ii); } while (0)
; DEV void scan_job(const P& p, int job, char* shm) {
;     ...
;       for (int i = 0; i < TC; i += 8) {
;         const int t8 = toff;
; #pragma unroll
;         for (int u = 0; u < 8; u += 2) {
;           toff += tstep; LOADOPS(B, toff); SBAR();
;           STEP(A, u); SBAR();
;           toff += tstep; if (i + u + 2 < TC) LOADOPS(A, toff);
;           SBAR();
;           STEP(B, u + 1); SBAR();
;         }
;         *reinterpret_cast<f32x2*>(Yy + t8 + np * tstep + 2 * rp) = f32x2{yk0, yk1};
	v_pk_fma_f32 v[110:111], v[28:29], v[124:125], v[110:111]
	v_pk_fma_f32 v[112:113], v[30:31], v[112:113], v[118:119]
	v_pk_mul_f32 v[118:119], v[8:9], v[116:117] op_sel_hi:[1,0] neg_lo:[0,1] neg_hi:[0,1]
	v_pk_mul_f32 v[116:117], v[10:11], v[116:117] op_sel_hi:[1,0] neg_lo:[0,1] neg_hi:[0,1]
	v_pk_fma_f32 v[110:111], v[98:99], v[20:21], v[110:111] op_sel_hi:[0,1,1]
	v_pk_fma_f32 v[112:113], v[98:99], v[22:23], v[112:113] op_sel_hi:[0,1,1]
	v_pk_fma_f32 v[114:115], v[0:1], v[114:115], v[118:119]
	v_pk_fma_f32 v[116:117], v[2:3], v[130:131], v[116:117]
	v_pk_fma_f32 v[114:115], v[98:99], v[12:13], v[114:115] op_sel_hi:[0,1,1]
	v_pk_fma_f32 v[116:117], v[98:99], v[14:15], v[116:117] op_sel_hi:[0,1,1]
	v_pk_mul_f32 v[118:119], v[16:17], v[110:111]
	v_pk_mul_f32 v[120:121], v[18:19], v[112:113]
	v_pk_fma_f32 v[118:119], v[4:5], v[114:115], v[118:119]
	v_pk_fma_f32 v[120:121], v[6:7], v[116:117], v[120:121]
	s_nop 0
	v_pk_add_f32 v[170:171], v[118:119], v[120:121]
	v_pk_mul_f32 v[118:119], v[36:37], v[134:135]
	v_pk_mul_f32 v[120:121], v[38:39], v[136:137]
	v_pk_fma_f32 v[118:119], v[32:33], v[162:163], v[118:119]
	v_pk_fma_f32 v[120:121], v[34:35], v[166:167], v[120:121]
	s_nop 0
	v_pk_add_f32 v[118:119], v[118:119], v[120:121]
	s_nop 0
	v_add_f32_e32 v118, v118, v119
	s_nop 1
	v_add_f32_dpp v118, v118, v118 quad_perm:[1,0,3,2] row_mask:0xf bank_mask:0xf bound_ctrl:1
	s_nop 1
	v_add_f32_dpp v118, v118, v118 quad_perm:[2,3,0,1] row_mask:0xf bank_mask:0xf bound_ctrl:1
	s_nop 1
	v_add_f32_dpp v124, v118, v118 row_half_mirror row_mask:0xf bank_mask:0xf bound_ctrl:1
	v_pk_mul_f32 v[118:119], v[24:25], v[124:125] op_sel_hi:[1,0] neg_lo:[0,1] neg_hi:[0,1]
	v_pk_mul_f32 v[120:121], v[26:27], v[124:125] op_sel_hi:[1,0] neg_lo:[0,1] neg_hi:[0,1]
	v_pk_fma_f32 v[118:119], v[28:29], v[134:135], v[118:119]
	v_pk_fma_f32 v[120:121], v[30:31], v[136:137], v[120:121]
	v_pk_mul_f32 v[122:123], v[8:9], v[124:125] op_sel_hi:[1,0] neg_lo:[0,1] neg_hi:[0,1]
	v_pk_mul_f32 v[124:125], v[10:11], v[124:125] op_sel_hi:[1,0] neg_lo:[0,1] neg_hi:[0,1]
	v_pk_fma_f32 v[118:119], v[98:99], v[20:21], v[118:119] op_sel:[1,0,0]
	v_pk_fma_f32 v[120:121], v[98:99], v[22:23], v[120:121] op_sel:[1,0,0]
	v_pk_fma_f32 v[122:123], v[0:1], v[162:163], v[122:123]
	v_pk_fma_f32 v[124:125], v[2:3], v[166:167], v[124:125]
	v_pk_fma_f32 v[122:123], v[98:99], v[12:13], v[122:123] op_sel:[1,0,0]
	v_pk_fma_f32 v[124:125], v[98:99], v[14:15], v[124:125] op_sel:[1,0,0]
	v_pk_mul_f32 v[130:131], v[16:17], v[118:119]
	v_pk_mul_f32 v[134:135], v[18:19], v[120:121]
	v_pk_fma_f32 v[130:131], v[4:5], v[122:123], v[130:131]
	v_pk_fma_f32 v[134:135], v[6:7], v[124:125], v[134:135]
	v_mov_b32_e32 v136, v170
	v_pk_add_f32 v[134:135], v[130:131], v[134:135]
	v_add_f32_e32 v94, v94, v95
	v_add_f32_e32 v95, v96, v97
	v_add_f32_e32 v100, v100, v101
	v_add_f32_e32 v101, v102, v103
	v_add_f32_e32 v106, v106, v107
	v_add_f32_e32 v107, v108, v109
	v_add_f32_e32 v126, v126, v127
	v_add_f32_e32 v127, v128, v129
	v_mov_b32_e32 v130, v132
	v_mov_b32_e32 v131, v168
	v_mov_b32_e32 v168, v133
	v_mov_b32_e32 v137, v134
	v_mov_b32_e32 v134, v171
	v_pk_add_f32 v[130:131], v[130:131], v[168:169]
	v_pk_add_f32 v[134:135], v[136:137], v[134:135]
	v_add_f32_dpp v94, v94, v94 quad_perm:[1,0,3,2] row_mask:0xf bank_mask:0xf bound_ctrl:1
	v_add_f32_dpp v95, v95, v95 quad_perm:[1,0,3,2] row_mask:0xf bank_mask:0xf bound_ctrl:1
	v_add_f32_dpp v100, v100, v100 quad_perm:[1,0,3,2] row_mask:0xf bank_mask:0xf bound_ctrl:1
	v_add_f32_dpp v101, v101, v101 quad_perm:[1,0,3,2] row_mask:0xf bank_mask:0xf bound_ctrl:1
	v_add_f32_dpp v106, v106, v106 quad_perm:[1,0,3,2] row_mask:0xf bank_mask:0xf bound_ctrl:1
	v_add_f32_dpp v107, v107, v107 quad_perm:[1,0,3,2] row_mask:0xf bank_mask:0xf bound_ctrl:1
	v_add_f32_dpp v126, v126, v126 quad_perm:[1,0,3,2] row_mask:0xf bank_mask:0xf bound_ctrl:1
	v_add_f32_dpp v127, v127, v127 quad_perm:[1,0,3,2] row_mask:0xf bank_mask:0xf bound_ctrl:1
	v_add_f32_dpp v130, v130, v130 quad_perm:[1,0,3,2] row_mask:0xf bank_mask:0xf bound_ctrl:1
	v_add_f32_dpp v131, v131, v131 quad_perm:[1,0,3,2] row_mask:0xf bank_mask:0xf bound_ctrl:1
	v_add_f32_dpp v134, v134, v134 quad_perm:[1,0,3,2] row_mask:0xf bank_mask:0xf bound_ctrl:1
	v_add_f32_dpp v135, v135, v135 quad_perm:[1,0,3,2] row_mask:0xf bank_mask:0xf bound_ctrl:1
	v_add_f32_dpp v94, v94, v94 quad_perm:[2,3,0,1] row_mask:0xf bank_mask:0xf bound_ctrl:1
	v_add_f32_dpp v95, v95, v95 quad_perm:[2,3,0,1] row_mask:0xf bank_mask:0xf bound_ctrl:1
	v_add_f32_dpp v100, v100, v100 quad_perm:[2,3,0,1] row_mask:0xf bank_mask:0xf bound_ctrl:1
	v_add_f32_dpp v101, v101, v101 quad_perm:[2,3,0,1] row_mask:0xf bank_mask:0xf bound_ctrl:1
	v_add_f32_dpp v106, v106, v106 quad_perm:[2,3,0,1] row_mask:0xf bank_mask:0xf bound_ctrl:1
	v_add_f32_dpp v107, v107, v107 quad_perm:[2,3,0,1] row_mask:0xf bank_mask:0xf bound_ctrl:1
	v_add_f32_dpp v126, v126, v126 quad_perm:[2,3,0,1] row_mask:0xf bank_mask:0xf bound_ctrl:1
	v_add_f32_dpp v127, v127, v127 quad_perm:[2,3,0,1] row_mask:0xf bank_mask:0xf bound_ctrl:1
	v_add_f32_dpp v130, v130, v130 quad_perm:[2,3,0,1] row_mask:0xf bank_mask:0xf bound_ctrl:1
	v_add_f32_dpp v131, v131, v131 quad_perm:[2,3,0,1] row_mask:0xf bank_mask:0xf bound_ctrl:1
	v_add_f32_dpp v134, v134, v134 quad_perm:[2,3,0,1] row_mask:0xf bank_mask:0xf bound_ctrl:1
	v_add_f32_dpp v135, v135, v135 quad_perm:[2,3,0,1] row_mask:0xf bank_mask:0xf bound_ctrl:1
	v_add_f32_dpp v96, v94, v94 row_half_mirror row_mask:0xf bank_mask:0xf bound_ctrl:1
	v_add_f32_dpp v97, v95, v95 row_half_mirror row_mask:0xf bank_mask:0xf bound_ctrl:1
	v_add_f32_dpp v102, v100, v100 row_half_mirror row_mask:0xf bank_mask:0xf bound_ctrl:1
	v_add_f32_dpp v103, v101, v101 row_half_mirror row_mask:0xf bank_mask:0xf bound_ctrl:1
	v_add_f32_dpp v108, v106, v106 row_half_mirror row_mask:0xf bank_mask:0xf bound_ctrl:1
	v_add_f32_dpp v109, v107, v107 row_half_mirror row_mask:0xf bank_mask:0xf bound_ctrl:1
	v_add_f32_dpp v128, v126, v126 row_half_mirror row_mask:0xf bank_mask:0xf bound_ctrl:1
	v_add_f32_dpp v129, v127, v127 row_half_mirror row_mask:0xf bank_mask:0xf bound_ctrl:1
	v_add_f32_dpp v132, v130, v130 row_half_mirror row_mask:0xf bank_mask:0xf bound_ctrl:1
	v_add_f32_dpp v133, v131, v131 row_half_mirror row_mask:0xf bank_mask:0xf bound_ctrl:1
	v_add_f32_dpp v136, v134, v134 row_half_mirror row_mask:0xf bank_mask:0xf bound_ctrl:1
	v_add_f32_dpp v137, v135, v135 row_half_mirror row_mask:0xf bank_mask:0xf bound_ctrl:1
	s_add_i32 s40, s45, 14
	s_cmp_gt_u32 s40, 29
	s_cbranch_scc1 .LBB0_1506
	ds_read_b128 v[0:3], v159 offset:16
	ds_read_b128 v[36:39], v159 offset:8704
	ds_read_b128 v[32:35], v159 offset:8720
	ds_read_b128 v[24:27], v159 offset:17408
	ds_read_b128 v[8:11], v159 offset:17424
	ds_read_b128 v[20:23], v159 offset:26112
	ds_read_b128 v[12:15], v159 offset:26128
	ds_read_b128 v[28:31], v159
	ds_read_b128 v[4:7], v159 offset:34832
	v_add_u32_e32 v98, s34, v157
	ds_read_b128 v[16:19], v159 offset:34816
	ds_read_b64 v[98:99], v98
	s_branch .LBB0_1506
